# att: one static s_setprio 1 for waves 4-7 for the whole attention phase
# baseline (speedup 1.0000x reference)
.LBB0_1244:
.LBB0_1245:
	v_readfirstlane_b32 s98, v194
	s_lshr_b32 s98, s98, 6
	s_cmp_lt_u32 s98, 4
	s_cbranch_scc1 .Lattprio_skip
	s_setprio 1

.LBB0_1298:
	s_setprio 0
	s_waitcnt vmcnt(0)
	s_waitcnt lgkmcnt(0)
	s_barrier
	s_and_saveexec_b64 s[6:7], s[28:29]
	s_cbranch_execz .LBB0_1350
	s_add_i32 s3, 0, 0x27fc0
	v_mov_b32_e32 v0, s3
	s_waitcnt vmcnt(0) expcnt(0) lgkmcnt(0)
	ds_read_b32 v2, v0
	s_add_i32 s3, 0, 0x27fc4
	v_mov_b32_e32 v0, s3
	ds_read_b32 v0, v0
	s_waitcnt lgkmcnt(1)
	v_cmp_ne_u32_e32 vcc, 0, v2
	s_cbranch_vccnz .LBB0_1314
	s_add_u32 s8, s10, 0x10200
	s_addc_u32 s9, s11, 0
	s_add_u32 s12, s10, 0x10400
	s_addc_u32 s13, s11, 0
	s_add_u32 s14, s10, 0x10500
	s_addc_u32 s15, s11, 0
	s_add_u32 s16, s10, 0x10600
	s_addc_u32 s17, s11, 0
	s_add_u32 s18, s10, 0x10700
	s_addc_u32 s19, s11, 0
	s_add_u32 s20, s10, 0x10800
	s_addc_u32 s21, s11, 0
	s_add_u32 s22, s10, 0x10900
	s_addc_u32 s23, s11, 0
	s_add_u32 s24, s10, 0x10a00
	s_addc_u32 s25, s11, 0
	s_add_u32 s26, s10, 0x10b00
	s_addc_u32 s27, s11, 0
	s_add_u32 s36, s10, 0x10c00
	s_addc_u32 s37, s11, 0
	s_add_u32 s38, s10, 0x10d00
	s_addc_u32 s39, s11, 0
	s_add_u32 s42, s10, 0x10e00
	s_addc_u32 s43, s11, 0
	s_add_u32 s44, s10, 0x10f00
	s_addc_u32 s45, s11, 0
	s_add_u32 s46, s10, 0x11000
	s_addc_u32 s47, s11, 0
	s_add_u32 s48, s10, 0x11100
	s_addc_u32 s49, s11, 0
	s_add_u32 s50, s10, 0x11200
	s_addc_u32 s51, s11, 0
	s_mul_i32 s3, s35, s78
	s_add_u32 s52, s10, 0x11300
	s_mul_i32 s3, s3, s34
	s_addc_u32 s53, s11, 0
	s_mov_b32 s31, 1
	v_mov_b32_e32 v16, 0
	s_branch .LBB0_1302
